# q/k tiles: the two 8-byte q/kn stores of a lane merged into one 16-byte store after a permlane16 row swap (7.3); final-phase wave_sum on DPP
# speedup vs baseline: 1.0066x; 1.0066x over previous
; #define GAS __attribute__((address_space(1)))
; __device__ __forceinline__ float bflo(unsigned u) { return __uint_as_float(u << 16); }
; __device__ __forceinline__ float bfhi(unsigned u) { return __uint_as_float(u & 0xffff0000u); }
; __device__ __forceinline__ void final_phase(const Args& A, Frame& F) {
;     ...
;     for (int r = F.bid * 8 + F.wave; r < NB * SEQ; r += F.G * 8) {
;         const int b = r >> 11, t = r & 2047;
;         const u32x2* xr = (const u32x2*)(WSB(WS_R) + ((size_t)b * TB + CTXL + t) * D) + F.lane;
;         f32x4 v[4]; float ss = 0.f;
; #pragma unroll
;         for (int j = 0; j < 4; ++j) { const u32x2 xv = xr[64 * j]; v[j][0] = bflo(xv.x); v[j][1] = bfhi(xv.x); v[j][2] = bflo(xv.y); v[j][3] = bfhi(xv.y); ss += (v[j][0] * v[j][0] + v[j][1] * v[j][1]) + (v[j][2] * v[j][2] + v[j][3] * v[j][3]); }
;         const float rstd = rsqrtf(wave_sum(ss) * (1.f / D) + EPS);
;         f32x4* o = (f32x4*)((float*)(GAS float*)(unsigned long long)A.out + (size_t)r * D) + F.lane;
; #pragma unroll
;         for (int j = 0; j < 4; ++j) { const f32x4 gv = *(const f32x4*)(g + 4 * (F.lane + 64 * j)); o[64 * j] = v[j] * rstd * gv; }
;     }
.LBB0_14:
	s_ashr_i32 s7, s2, 11
	s_and_b32 s10, s2, 0x7ff
	s_mul_hi_i32 s11, s7, 0x900
	s_mulk_i32 s7, 0x900
	s_addk_i32 s10, 0x100
	s_add_u32 s10, s7, s10
	s_addc_u32 s11, s11, 0
	s_lshl_b64 s[10:11], s[10:11], 11
	v_lshl_add_u64 v[14:15], v[2:3], 0, s[10:11]
	global_load_dwordx2 v[18:19], v[14:15], off
	global_load_dwordx2 v[20:21], v[14:15], off offset:512
	global_load_dwordx2 v[22:23], v[14:15], off offset:1024
	global_load_dwordx2 v[24:25], v[14:15], off offset:1536
	s_nop 0
	global_load_dwordx4 v[14:17], v[4:5], off
	s_add_i32 s2, s2, s6
	s_cmpk_gt_i32 s2, 0x3fff
	s_waitcnt vmcnt(0)
	v_lshlrev_b32_e32 v26, 16, v18
	v_and_b32_e32 v27, 0xffff0000, v18
	v_lshlrev_b32_e32 v18, 16, v19
	v_and_b32_e32 v19, 0xffff0000, v19
	s_waitcnt vmcnt(3)
	v_lshlrev_b32_e32 v29, 16, v21
	v_lshlrev_b32_e32 v28, 16, v20
	v_and_b32_e32 v21, 0xffff0000, v21
	v_and_b32_e32 v20, 0xffff0000, v20
	s_waitcnt vmcnt(2)
	v_lshlrev_b32_e32 v30, 16, v22
	v_and_b32_e32 v31, 0xffff0000, v22
	v_lshlrev_b32_e32 v22, 16, v23
	v_and_b32_e32 v23, 0xffff0000, v23
	s_waitcnt vmcnt(1)
	v_lshlrev_b32_e32 v33, 16, v24
	v_mul_f32_e32 v0, v19, v19
	v_mul_f32_e32 v32, v27, v27
	v_pk_mul_f32 v[36:37], v[20:21], v[20:21]
	v_mov_b32_e32 v39, v33
	v_mul_f32_e32 v38, v23, v23
	v_pk_fma_f32 v[40:41], v[18:19], v[18:19], v[0:1] op_sel_hi:[1,1,0]
	v_pk_fma_f32 v[42:43], v[26:27], v[26:27], v[32:33] op_sel_hi:[1,1,0]
	v_and_b32_e32 v35, 0xffff0000, v24
	v_lshlrev_b32_e32 v24, 16, v25
	v_and_b32_e32 v25, 0xffff0000, v25
	v_mul_f32_e32 v34, v31, v31
	v_pk_fma_f32 v[36:37], v[28:29], v[28:29], v[36:37]
	v_pk_fma_f32 v[46:47], v[22:23], v[22:23], v[38:39] op_sel_hi:[1,1,0]
	v_mov_b32_e32 v32, v42
	v_mov_b32_e32 v38, v40
	v_mul_f32_e32 v48, v35, v35
	v_mul_f32_e32 v49, v24, v24
	v_mul_f32_e32 v50, v25, v25
	v_pk_fma_f32 v[44:45], v[30:31], v[30:31], v[34:35] op_sel_hi:[1,1,0]
	v_pk_add_f32 v[40:41], v[42:43], v[40:41]
	v_pk_add_f32 v[36:37], v[36:37], v[36:37] op_sel:[0,1] op_sel_hi:[1,0]
	v_pk_mul_f32 v[38:39], v[32:33], v[38:39]
	v_mov_b32_e32 v45, v49
	v_mov_b32_e32 v47, v50
	v_mov_b32_e32 v37, v48
	v_mov_b32_e32 v41, v39
	v_pk_add_f32 v[42:43], v[44:45], v[46:47]
	v_pk_add_f32 v[36:37], v[40:41], v[36:37]
	v_mov_b32_e32 v34, v33
	v_pk_add_f32 v[36:37], v[36:37], v[42:43]
	s_nop 0
	v_add_f32_e32 v0, v36, v37
	s_nop 1
	v_add_f32_dpp v0, v0, v0 quad_perm:[1,0,3,2] row_mask:0xf bank_mask:0xf
	s_nop 1
	v_add_f32_dpp v0, v0, v0 quad_perm:[2,3,0,1] row_mask:0xf bank_mask:0xf
	s_nop 1
	v_add_f32_dpp v0, v0, v0 row_half_mirror row_mask:0xf bank_mask:0xf
	s_nop 1
	v_add_f32_dpp v0, v0, v0 row_mirror row_mask:0xf bank_mask:0xf
	v_mov_b32_e32 v32, v0
	s_nop 1
	v_permlane16_swap_b32 v0, v32
	v_add_f32_e32 v0, v0, v32
	v_mov_b32_e32 v32, v0
	s_nop 1
	v_permlane32_swap_b32 v0, v32
	v_add_f32_e32 v0, v0, v32
	v_fmamk_f32 v0, v0, 0x3a800000, v170
	v_mul_f32_e32 v32, 0x4b800000, v0
	v_cmp_gt_f32_e32 vcc, s33, v0
	s_nop 1
	v_cndmask_b32_e32 v0, v0, v32, vcc
	v_rsq_f32_e32 v0, v0
	s_nop 0
	v_mul_f32_e32 v32, 0x45800000, v0
	v_cndmask_b32_e32 v0, v0, v32, vcc
	v_pk_mul_f32 v[26:27], v[0:1], v[26:27] op_sel_hi:[0,1]
	v_pk_mul_f32 v[18:19], v[0:1], v[18:19] op_sel_hi:[0,1]
	s_waitcnt vmcnt(0)
	v_pk_mul_f32 v[16:17], v[16:17], v[18:19]
	v_pk_mul_f32 v[14:15], v[14:15], v[26:27]
	global_store_dwordx4 v[6:7], v[14:17], off offset:-3072
	global_load_dwordx4 v[14:17], v[4:5], off offset:1024
	v_mov_b32_e32 v18, v29
	v_mov_b32_e32 v19, v21
	v_mov_b32_e32 v29, v20
	v_pk_mul_f32 v[18:19], v[0:1], v[18:19] op_sel_hi:[0,1]
	v_pk_mul_f32 v[20:21], v[0:1], v[28:29] op_sel_hi:[0,1]
	s_waitcnt vmcnt(0)
	v_pk_mul_f32 v[14:15], v[14:15], v[20:21]
	v_pk_mul_f32 v[16:17], v[16:17], v[18:19]
	global_store_dwordx4 v[6:7], v[14:17], off offset:-2048
	global_load_dwordx4 v[14:17], v[4:5], off offset:2048
	v_pk_mul_f32 v[18:19], v[0:1], v[22:23] op_sel_hi:[0,1]
	v_pk_mul_f32 v[20:21], v[0:1], v[30:31] op_sel_hi:[0,1]
	s_waitcnt vmcnt(0)
	v_pk_mul_f32 v[14:15], v[14:15], v[20:21]
	v_pk_mul_f32 v[16:17], v[16:17], v[18:19]
	global_store_dwordx4 v[6:7], v[14:17], off offset:-1024
	global_load_dwordx4 v[14:17], v[4:5], off offset:3072
	v_pk_mul_f32 v[18:19], v[24:25], v[0:1] op_sel_hi:[1,0]
	v_pk_mul_f32 v[20:21], v[34:35], v[0:1] op_sel_hi:[1,0]
	s_waitcnt vmcnt(0)
	v_pk_mul_f32 v[16:17], v[16:17], v[18:19]
	v_pk_mul_f32 v[14:15], v[14:15], v[20:21]
	global_store_dwordx4 v[6:7], v[14:17], off
	v_lshl_add_u64 v[6:7], v[6:7], 0, s[8:9]
	s_cbranch_scc0 .LBB0_14

;     __device__ __forceinline__ void operator()(const AccT& acc, const pg8::Unit& u, int wr, int wc, int fr_, int fq_) const {
;     ...
;         const int rl0 = wr * 64 + fr;
;         if (pn < 4) {
;             const bool isk = pn >= 2;
;             const int jj0 = 16 * (wc & 1) + 4 * fq;
; #pragma unroll
;             for (int ai = 0; ai < 2; ++ai)
; #pragma unroll
;                 for (int m = 0; m < 4; ++m) {
;                     const int rl = rl0 + ai * 128 + m * 16;
;                     const size_t row = (size_t)u.pm * 256 + rl;
;                     f32x4 cs = (f32x4){1.f, 1.f, 1.f, 1.f}, sn = (f32x4){0.f, 0.f, 0.f, 0.f};
;                     if (pt != 0) { const int tpos = (pt - 1) * 256 + rl; cs = *(const f32x4*)(rope + (size_t)tpos * 32 + jj0); sn = *(const f32x4*)(rope + (size_t)SEQ * 32 + (size_t)tpos * 32 + jj0); }
.LBB0_266:
	v_readlane_b32 s2, v254, 38
	v_readlane_b32 s98, v254, 32
	v_readlane_b32 s99, v254, 33
	v_readlane_b32 s15, v254, 36
	s_nop 1
	v_lshl_add_u32 v154, v156, 2, s2
	v_lshlrev_b32_e32 v153, 2, v154
	v_lshl_add_u32 v153, v152, 7, v153
	v_lshlrev_b32_e32 v189, 1, v154
	v_lshl_add_u32 v189, v152, 10, v189
	v_and_b32_e32 v155, 1, v156
	v_mul_u32_u24_e32 v155, 56, v155
	v_add_u32_e32 v189, v189, v155
	v_mul_u32_u24_e32 v238, 0x1200, v154
	v_lshl_add_u32 v238, v152, 1, v238
	s_cmp_eq_u32 s71, 0
	s_cbranch_scc1 .Lqk_norope
	s_add_i32 s4, s71, -1
	s_lshl_b32 s4, s4, 15
	s_add_u32 s98, s98, s4
	s_addc_u32 s99, s99, 0
	s_add_u32 s100, s18, s4
	s_addc_u32 s101, s19, 0
	v_add_u32_e32 v155, 0x1000, v153
	v_add_u32_e32 v157, 0x4000, v153
	v_add_u32_e32 v168, 0x5000, v153
	global_load_dwordx4 v[190:193], v153, s[98:99]
	global_load_dwordx4 v[194:197], v153, s[100:101]
	global_load_dwordx4 v[198:201], v153, s[98:99] offset:2048
	global_load_dwordx4 v[202:205], v153, s[100:101] offset:2048
	global_load_dwordx4 v[206:209], v155, s[98:99]
	global_load_dwordx4 v[210:213], v155, s[100:101]
	global_load_dwordx4 v[214:217], v155, s[98:99] offset:2048
	global_load_dwordx4 v[218:221], v155, s[100:101] offset:2048
	global_load_dwordx4 v[222:225], v157, s[98:99]
	global_load_dwordx4 v[226:229], v157, s[100:101]
	global_load_dwordx4 v[230:233], v157, s[98:99] offset:2048
	global_load_dwordx4 v[234:237], v157, s[100:101] offset:2048
	global_load_dwordx4 v[130:133], v168, s[98:99]
	global_load_dwordx4 v[134:137], v168, s[100:101]
	global_load_dwordx4 v[158:161], v168, s[98:99] offset:2048
	global_load_dwordx4 v[162:165], v168, s[100:101] offset:2048
	s_branch .Lqk_go

; __device__ __forceinline__ unsigned pk2(float lo, float hi) { const f32x2_t v = {lo, hi}; const bf16v2_t b = __builtin_convertvector(v, bf16v2_t); return __builtin_bit_cast(unsigned, b); }
;     __device__ __forceinline__ void operator()(const AccT& acc, const pg8::Unit& u, int wr, int wc, int fr_, int fq_) const {
;     ...
;         if (pn < 4) {
;             const bool isk = pn >= 2;
;             const int jj0 = 16 * (wc & 1) + 4 * fq;
; #pragma unroll
;             for (int ai = 0; ai < 2; ++ai)
; #pragma unroll
;                 for (int m = 0; m < 4; ++m) {
;                     const int rl = rl0 + ai * 128 + m * 16;
;                     const size_t row = (size_t)u.pm * 256 + rl;
;                     f32x4 cs = (f32x4){1.f, 1.f, 1.f, 1.f}, sn = (f32x4){0.f, 0.f, 0.f, 0.f};
;                     if (pt != 0) { const int tpos = (pt - 1) * 256 + rl; cs = *(const f32x4*)(rope + (size_t)tpos * 32 + jj0); sn = *(const f32x4*)(rope + (size_t)SEQ * 32 + (size_t)tpos * 32 + jj0); }
; #pragma unroll
;                     for (int bj = 0; bj < 2; ++bj) {
;                         const int hq = 4 * (pn & 1) + 2 * bj + (wc >> 1);
;                         const f32x4 a1 = acc[ai][bj][m][0], a2 = acc[ai][bj][m][1];
;                         f32x4 o1 = a1 * cs - a2 * sn, o2 = a1 * sn + a2 * cs;
;                         if (isk) { o1 *= 0.125f; o2 *= 0.125f; }
;                         u32x2 p1, p2; p1.x = pk2(o1[0], o1[1]); p1.y = pk2(o1[2], o1[3]); p2.x = pk2(o2[0], o2[1]); p2.y = pk2(o2[2], o2[3]);
;                         bf16_t* dst = (isk ? KN : Q) + row * 512 + hq * 64 + jj0;
;                         *(u32x2*)dst = p1; *(u32x2*)(dst + 32) = p2;
.Lqk_go:
	s_and_b32 s2, s52, 1
	s_lshl_b32 s2, s2, 2
	s_or_b32 s15, s15, s2
	s_cmp_gt_i32 s52, 1
	s_mov_b32 s2, 0xb4c8000
	s_cselect_b32 s2, s2, 0xa2c8000
	s_add_u32 s78, s30, s2
	s_addc_u32 s79, s31, 0
	s_lshl_b32 s2, s14, 18
	s_add_u32 s78, s78, s2
	s_addc_u32 s79, s79, 0
	s_lshl_b32 s2, s15, 7
	s_add_u32 s78, s78, s2
	s_addc_u32 s79, s79, 0
	s_cmp_gt_i32 s52, 1
	s_cbranch_scc1 .Lqk_k
	s_waitcnt vmcnt(0)
	v_pk_mul_f32 v[152:153], v[126:127], v[194:195]
	v_pk_mul_f32 v[154:155], v[128:129], v[196:197]
	v_pk_mul_f32 v[126:127], v[126:127], v[190:191]
	v_pk_mul_f32 v[128:129], v[128:129], v[192:193]
	v_pk_fma_f32 v[152:153], v[122:123], v[190:191], v[152:153] neg_lo:[0,0,1] neg_hi:[0,0,1]
	v_pk_fma_f32 v[154:155], v[124:125], v[192:193], v[154:155] neg_lo:[0,0,1] neg_hi:[0,0,1]
	v_pk_fma_f32 v[126:127], v[122:123], v[194:195], v[126:127]
	v_pk_fma_f32 v[128:129], v[124:125], v[196:197], v[128:129]
	v_cvt_pk_bf16_f32 v122, v152, v153
	v_cvt_pk_bf16_f32 v123, v154, v155
	v_cvt_pk_bf16_f32 v124, v126, v127
	v_cvt_pk_bf16_f32 v125, v128, v129
	s_nop 1
	v_permlane16_swap_b32 v122, v124
	v_permlane16_swap_b32 v123, v125
	global_store_dwordx4 v189, v[122:125], s[78:79]
	v_pk_mul_f32 v[156:157], v[110:111], v[202:203]
	v_pk_mul_f32 v[168:169], v[112:113], v[204:205]
	v_pk_mul_f32 v[110:111], v[110:111], v[198:199]
	v_pk_mul_f32 v[112:113], v[112:113], v[200:201]
	v_pk_fma_f32 v[156:157], v[106:107], v[198:199], v[156:157] neg_lo:[0,0,1] neg_hi:[0,0,1]
	v_pk_fma_f32 v[168:169], v[108:109], v[200:201], v[168:169] neg_lo:[0,0,1] neg_hi:[0,0,1]
	v_pk_fma_f32 v[110:111], v[106:107], v[202:203], v[110:111]
	v_pk_fma_f32 v[112:113], v[108:109], v[204:205], v[112:113]
	v_cvt_pk_bf16_f32 v106, v156, v157
	v_cvt_pk_bf16_f32 v107, v168, v169
	v_cvt_pk_bf16_f32 v108, v110, v111
	v_cvt_pk_bf16_f32 v109, v112, v113
	v_add_u32_e32 v239, 0x4000, v189
	s_nop 1
	v_permlane16_swap_b32 v106, v108
	v_permlane16_swap_b32 v107, v109
	global_store_dwordx4 v239, v[106:109], s[78:79]
	v_pk_mul_f32 v[152:153], v[94:95], v[210:211]
	v_pk_mul_f32 v[154:155], v[96:97], v[212:213]
	v_pk_mul_f32 v[94:95], v[94:95], v[206:207]
	v_pk_mul_f32 v[96:97], v[96:97], v[208:209]
	v_pk_fma_f32 v[152:153], v[90:91], v[206:207], v[152:153] neg_lo:[0,0,1] neg_hi:[0,0,1]
	v_pk_fma_f32 v[154:155], v[92:93], v[208:209], v[154:155] neg_lo:[0,0,1] neg_hi:[0,0,1]
	v_pk_fma_f32 v[94:95], v[90:91], v[210:211], v[94:95]
	v_pk_fma_f32 v[96:97], v[92:93], v[212:213], v[96:97]
	v_cvt_pk_bf16_f32 v90, v152, v153
	v_cvt_pk_bf16_f32 v91, v154, v155
	v_cvt_pk_bf16_f32 v92, v94, v95
	v_cvt_pk_bf16_f32 v93, v96, v97
	v_add_u32_e32 v239, 0x8000, v189
	s_nop 1
	v_permlane16_swap_b32 v90, v92
	v_permlane16_swap_b32 v91, v93
	global_store_dwordx4 v239, v[90:93], s[78:79]
	v_pk_mul_f32 v[156:157], v[78:79], v[218:219]
	v_pk_mul_f32 v[168:169], v[80:81], v[220:221]
	v_pk_mul_f32 v[78:79], v[78:79], v[214:215]
	v_pk_mul_f32 v[80:81], v[80:81], v[216:217]
	v_pk_fma_f32 v[156:157], v[74:75], v[214:215], v[156:157] neg_lo:[0,0,1] neg_hi:[0,0,1]
	v_pk_fma_f32 v[168:169], v[76:77], v[216:217], v[168:169] neg_lo:[0,0,1] neg_hi:[0,0,1]
	v_pk_fma_f32 v[78:79], v[74:75], v[218:219], v[78:79]
	v_pk_fma_f32 v[80:81], v[76:77], v[220:221], v[80:81]
	v_cvt_pk_bf16_f32 v74, v156, v157
	v_cvt_pk_bf16_f32 v75, v168, v169
	v_cvt_pk_bf16_f32 v76, v78, v79
	v_cvt_pk_bf16_f32 v77, v80, v81
	v_add_u32_e32 v239, 0xc000, v189
	s_nop 1
	v_permlane16_swap_b32 v74, v76
	v_permlane16_swap_b32 v75, v77
	global_store_dwordx4 v239, v[74:77], s[78:79]
	v_pk_mul_f32 v[152:153], v[62:63], v[226:227]
	v_pk_mul_f32 v[154:155], v[64:65], v[228:229]
	v_pk_mul_f32 v[62:63], v[62:63], v[222:223]
	v_pk_mul_f32 v[64:65], v[64:65], v[224:225]
	v_pk_fma_f32 v[152:153], v[58:59], v[222:223], v[152:153] neg_lo:[0,0,1] neg_hi:[0,0,1]
	v_pk_fma_f32 v[154:155], v[60:61], v[224:225], v[154:155] neg_lo:[0,0,1] neg_hi:[0,0,1]
	v_pk_fma_f32 v[62:63], v[58:59], v[226:227], v[62:63]
	v_pk_fma_f32 v[64:65], v[60:61], v[228:229], v[64:65]
	v_cvt_pk_bf16_f32 v58, v152, v153
	v_cvt_pk_bf16_f32 v59, v154, v155
	v_cvt_pk_bf16_f32 v60, v62, v63
	v_cvt_pk_bf16_f32 v61, v64, v65
	v_add_u32_e32 v239, 0x20000, v189
	s_nop 1
	v_permlane16_swap_b32 v58, v60
	v_permlane16_swap_b32 v59, v61
	global_store_dwordx4 v239, v[58:61], s[78:79]
	v_pk_mul_f32 v[156:157], v[46:47], v[234:235]
	v_pk_mul_f32 v[168:169], v[48:49], v[236:237]
	v_pk_mul_f32 v[46:47], v[46:47], v[230:231]
	v_pk_mul_f32 v[48:49], v[48:49], v[232:233]
	v_pk_fma_f32 v[156:157], v[42:43], v[230:231], v[156:157] neg_lo:[0,0,1] neg_hi:[0,0,1]
	v_pk_fma_f32 v[168:169], v[44:45], v[232:233], v[168:169] neg_lo:[0,0,1] neg_hi:[0,0,1]
	v_pk_fma_f32 v[46:47], v[42:43], v[234:235], v[46:47]
	v_pk_fma_f32 v[48:49], v[44:45], v[236:237], v[48:49]
	v_cvt_pk_bf16_f32 v42, v156, v157
	v_cvt_pk_bf16_f32 v43, v168, v169
	v_cvt_pk_bf16_f32 v44, v46, v47
	v_cvt_pk_bf16_f32 v45, v48, v49
	v_add_u32_e32 v239, 0x24000, v189
	s_nop 1
	v_permlane16_swap_b32 v42, v44
	v_permlane16_swap_b32 v43, v45
	global_store_dwordx4 v239, v[42:45], s[78:79]
	v_pk_mul_f32 v[152:153], v[30:31], v[134:135]
	v_pk_mul_f32 v[154:155], v[32:33], v[136:137]
	v_pk_mul_f32 v[30:31], v[30:31], v[130:131]
	v_pk_mul_f32 v[32:33], v[32:33], v[132:133]
	v_pk_fma_f32 v[152:153], v[26:27], v[130:131], v[152:153] neg_lo:[0,0,1] neg_hi:[0,0,1]
	v_pk_fma_f32 v[154:155], v[28:29], v[132:133], v[154:155] neg_lo:[0,0,1] neg_hi:[0,0,1]
	v_pk_fma_f32 v[30:31], v[26:27], v[134:135], v[30:31]
	v_pk_fma_f32 v[32:33], v[28:29], v[136:137], v[32:33]
	v_cvt_pk_bf16_f32 v26, v152, v153
	v_cvt_pk_bf16_f32 v27, v154, v155
	v_cvt_pk_bf16_f32 v28, v30, v31
	v_cvt_pk_bf16_f32 v29, v32, v33
; __device__ __forceinline__ unsigned pk2(float lo, float hi) { const f32x2_t v = {lo, hi}; const bf16v2_t b = __builtin_convertvector(v, bf16v2_t); return __builtin_bit_cast(unsigned, b); }
;     __device__ __forceinline__ void operator()(const AccT& acc, const pg8::Unit& u, int wr, int wc, int fr_, int fq_) const {
;     ...
; #pragma unroll
;                     for (int bj = 0; bj < 2; ++bj) {
;                         const int hq = 4 * (pn & 1) + 2 * bj + (wc >> 1);
;                         const f32x4 a1 = acc[ai][bj][m][0], a2 = acc[ai][bj][m][1];
;                         f32x4 o1 = a1 * cs - a2 * sn, o2 = a1 * sn + a2 * cs;
;                         if (isk) { o1 *= 0.125f; o2 *= 0.125f; }
;                         u32x2 p1, p2; p1.x = pk2(o1[0], o1[1]); p1.y = pk2(o1[2], o1[3]); p2.x = pk2(o2[0], o2[1]); p2.y = pk2(o2[2], o2[3]);
;                         bf16_t* dst = (isk ? KN : Q) + row * 512 + hq * 64 + jj0;
;                         *(u32x2*)dst = p1; *(u32x2*)(dst + 32) = p2;
	v_add_u32_e32 v239, 0x28000, v189
	s_nop 1
	v_permlane16_swap_b32 v26, v28
	v_permlane16_swap_b32 v27, v29
	global_store_dwordx4 v239, v[26:29], s[78:79]
	v_pk_mul_f32 v[156:157], v[14:15], v[162:163]
	v_pk_mul_f32 v[168:169], v[16:17], v[164:165]
	v_pk_mul_f32 v[14:15], v[14:15], v[158:159]
	v_pk_mul_f32 v[16:17], v[16:17], v[160:161]
	v_pk_fma_f32 v[156:157], v[10:11], v[158:159], v[156:157] neg_lo:[0,0,1] neg_hi:[0,0,1]
	v_pk_fma_f32 v[168:169], v[12:13], v[160:161], v[168:169] neg_lo:[0,0,1] neg_hi:[0,0,1]
	v_pk_fma_f32 v[14:15], v[10:11], v[162:163], v[14:15]
	v_pk_fma_f32 v[16:17], v[12:13], v[164:165], v[16:17]
	v_cvt_pk_bf16_f32 v10, v156, v157
	v_cvt_pk_bf16_f32 v11, v168, v169
	v_cvt_pk_bf16_f32 v12, v14, v15
	v_cvt_pk_bf16_f32 v13, v16, v17
	v_add_u32_e32 v239, 0x2c000, v189
	s_nop 1
	v_permlane16_swap_b32 v10, v12
	v_permlane16_swap_b32 v11, v13
	global_store_dwordx4 v239, v[10:13], s[78:79]
	v_pk_mul_f32 v[152:153], v[118:119], v[194:195]
	v_pk_mul_f32 v[154:155], v[120:121], v[196:197]
	v_pk_mul_f32 v[118:119], v[118:119], v[190:191]
	v_pk_mul_f32 v[120:121], v[120:121], v[192:193]
	v_pk_fma_f32 v[152:153], v[114:115], v[190:191], v[152:153] neg_lo:[0,0,1] neg_hi:[0,0,1]
	v_pk_fma_f32 v[154:155], v[116:117], v[192:193], v[154:155] neg_lo:[0,0,1] neg_hi:[0,0,1]
	v_pk_fma_f32 v[118:119], v[114:115], v[194:195], v[118:119]
	v_pk_fma_f32 v[120:121], v[116:117], v[196:197], v[120:121]
	v_cvt_pk_bf16_f32 v114, v152, v153
	v_cvt_pk_bf16_f32 v115, v154, v155
	v_cvt_pk_bf16_f32 v116, v118, v119
	v_cvt_pk_bf16_f32 v117, v120, v121
	s_nop 1
	v_permlane16_swap_b32 v114, v116
	v_permlane16_swap_b32 v115, v117
	global_store_dwordx4 v189, v[114:117], s[78:79] offset:256
	v_pk_mul_f32 v[156:157], v[102:103], v[202:203]
	v_pk_mul_f32 v[168:169], v[104:105], v[204:205]
	v_pk_mul_f32 v[102:103], v[102:103], v[198:199]
	v_pk_mul_f32 v[104:105], v[104:105], v[200:201]
	v_pk_fma_f32 v[156:157], v[98:99], v[198:199], v[156:157] neg_lo:[0,0,1] neg_hi:[0,0,1]
	v_pk_fma_f32 v[168:169], v[100:101], v[200:201], v[168:169] neg_lo:[0,0,1] neg_hi:[0,0,1]
	v_pk_fma_f32 v[102:103], v[98:99], v[202:203], v[102:103]
	v_pk_fma_f32 v[104:105], v[100:101], v[204:205], v[104:105]
	v_cvt_pk_bf16_f32 v98, v156, v157
	v_cvt_pk_bf16_f32 v99, v168, v169
	v_cvt_pk_bf16_f32 v100, v102, v103
	v_cvt_pk_bf16_f32 v101, v104, v105
	v_add_u32_e32 v239, 0x4000, v189
	s_nop 1
	v_permlane16_swap_b32 v98, v100
	v_permlane16_swap_b32 v99, v101
	global_store_dwordx4 v239, v[98:101], s[78:79] offset:256
	v_pk_mul_f32 v[152:153], v[86:87], v[210:211]
	v_pk_mul_f32 v[154:155], v[88:89], v[212:213]
	v_pk_mul_f32 v[86:87], v[86:87], v[206:207]
	v_pk_mul_f32 v[88:89], v[88:89], v[208:209]
	v_pk_fma_f32 v[152:153], v[82:83], v[206:207], v[152:153] neg_lo:[0,0,1] neg_hi:[0,0,1]
	v_pk_fma_f32 v[154:155], v[84:85], v[208:209], v[154:155] neg_lo:[0,0,1] neg_hi:[0,0,1]
	v_pk_fma_f32 v[86:87], v[82:83], v[210:211], v[86:87]
	v_pk_fma_f32 v[88:89], v[84:85], v[212:213], v[88:89]
	v_cvt_pk_bf16_f32 v82, v152, v153
	v_cvt_pk_bf16_f32 v83, v154, v155
	v_cvt_pk_bf16_f32 v84, v86, v87
	v_cvt_pk_bf16_f32 v85, v88, v89
	v_add_u32_e32 v239, 0x8000, v189
	s_nop 1
	v_permlane16_swap_b32 v82, v84
	v_permlane16_swap_b32 v83, v85
	global_store_dwordx4 v239, v[82:85], s[78:79] offset:256
	v_pk_mul_f32 v[156:157], v[70:71], v[218:219]
	v_pk_mul_f32 v[168:169], v[72:73], v[220:221]
	v_pk_mul_f32 v[70:71], v[70:71], v[214:215]
	v_pk_mul_f32 v[72:73], v[72:73], v[216:217]
	v_pk_fma_f32 v[156:157], v[66:67], v[214:215], v[156:157] neg_lo:[0,0,1] neg_hi:[0,0,1]
	v_pk_fma_f32 v[168:169], v[68:69], v[216:217], v[168:169] neg_lo:[0,0,1] neg_hi:[0,0,1]
	v_pk_fma_f32 v[70:71], v[66:67], v[218:219], v[70:71]
	v_pk_fma_f32 v[72:73], v[68:69], v[220:221], v[72:73]
	v_cvt_pk_bf16_f32 v66, v156, v157
	v_cvt_pk_bf16_f32 v67, v168, v169
	v_cvt_pk_bf16_f32 v68, v70, v71
	v_cvt_pk_bf16_f32 v69, v72, v73
	v_add_u32_e32 v239, 0xc000, v189
	s_nop 1
	v_permlane16_swap_b32 v66, v68
	v_permlane16_swap_b32 v67, v69
	global_store_dwordx4 v239, v[66:69], s[78:79] offset:256
	v_pk_mul_f32 v[152:153], v[54:55], v[226:227]
	v_pk_mul_f32 v[154:155], v[56:57], v[228:229]
	v_pk_mul_f32 v[54:55], v[54:55], v[222:223]
	v_pk_mul_f32 v[56:57], v[56:57], v[224:225]
	v_pk_fma_f32 v[152:153], v[50:51], v[222:223], v[152:153] neg_lo:[0,0,1] neg_hi:[0,0,1]
	v_pk_fma_f32 v[154:155], v[52:53], v[224:225], v[154:155] neg_lo:[0,0,1] neg_hi:[0,0,1]
	v_pk_fma_f32 v[54:55], v[50:51], v[226:227], v[54:55]
	v_pk_fma_f32 v[56:57], v[52:53], v[228:229], v[56:57]
	v_cvt_pk_bf16_f32 v50, v152, v153
	v_cvt_pk_bf16_f32 v51, v154, v155
	v_cvt_pk_bf16_f32 v52, v54, v55
	v_cvt_pk_bf16_f32 v53, v56, v57
	v_add_u32_e32 v239, 0x20000, v189
	s_nop 1
	v_permlane16_swap_b32 v50, v52
	v_permlane16_swap_b32 v51, v53
	global_store_dwordx4 v239, v[50:53], s[78:79] offset:256
	v_pk_mul_f32 v[156:157], v[38:39], v[234:235]
	v_pk_mul_f32 v[168:169], v[40:41], v[236:237]
	v_pk_mul_f32 v[38:39], v[38:39], v[230:231]
	v_pk_mul_f32 v[40:41], v[40:41], v[232:233]
	v_pk_fma_f32 v[156:157], v[34:35], v[230:231], v[156:157] neg_lo:[0,0,1] neg_hi:[0,0,1]
	v_pk_fma_f32 v[168:169], v[36:37], v[232:233], v[168:169] neg_lo:[0,0,1] neg_hi:[0,0,1]
	v_pk_fma_f32 v[38:39], v[34:35], v[234:235], v[38:39]
	v_pk_fma_f32 v[40:41], v[36:37], v[236:237], v[40:41]
	v_cvt_pk_bf16_f32 v34, v156, v157
	v_cvt_pk_bf16_f32 v35, v168, v169
	v_cvt_pk_bf16_f32 v36, v38, v39
	v_cvt_pk_bf16_f32 v37, v40, v41
	v_add_u32_e32 v239, 0x24000, v189
	s_nop 1
	v_permlane16_swap_b32 v34, v36
	v_permlane16_swap_b32 v35, v37
	global_store_dwordx4 v239, v[34:37], s[78:79] offset:256
	v_pk_mul_f32 v[152:153], v[22:23], v[134:135]
; __device__ __forceinline__ unsigned pk2(float lo, float hi) { const f32x2_t v = {lo, hi}; const bf16v2_t b = __builtin_convertvector(v, bf16v2_t); return __builtin_bit_cast(unsigned, b); }
;     __device__ __forceinline__ void operator()(const AccT& acc, const pg8::Unit& u, int wr, int wc, int fr_, int fq_) const {
;     ...
; #pragma unroll
;                     for (int bj = 0; bj < 2; ++bj) {
;                         const int hq = 4 * (pn & 1) + 2 * bj + (wc >> 1);
;                         const f32x4 a1 = acc[ai][bj][m][0], a2 = acc[ai][bj][m][1];
;                         f32x4 o1 = a1 * cs - a2 * sn, o2 = a1 * sn + a2 * cs;
;                         if (isk) { o1 *= 0.125f; o2 *= 0.125f; }
;                         u32x2 p1, p2; p1.x = pk2(o1[0], o1[1]); p1.y = pk2(o1[2], o1[3]); p2.x = pk2(o2[0], o2[1]); p2.y = pk2(o2[2], o2[3]);
;                         bf16_t* dst = (isk ? KN : Q) + row * 512 + hq * 64 + jj0;
;                         *(u32x2*)dst = p1; *(u32x2*)(dst + 32) = p2;
;                         if (isk) {
;                             bf16_t* kt = KT + ((size_t)(b * NH + hq) * DK + jj0) * TB + pt * 256 + rl;
;                             kt[0] = (bf16_t)(p1.x & 0xffffu); kt[(size_t)TB] = (bf16_t)(p1.x >> 16); kt[(size_t)2 * TB] = (bf16_t)(p1.y & 0xffffu); kt[(size_t)3 * TB] = (bf16_t)(p1.y >> 16);
;                             bf16_t* kt2 = kt + (size_t)32 * TB;
;                             kt2[0] = (bf16_t)(p2.x & 0xffffu); kt2[(size_t)TB] = (bf16_t)(p2.x >> 16); kt2[(size_t)2 * TB] = (bf16_t)(p2.y & 0xffffu); kt2[(size_t)3 * TB] = (bf16_t)(p2.y >> 16);
;                         }
	v_pk_mul_f32 v[154:155], v[24:25], v[136:137]
	v_pk_mul_f32 v[22:23], v[22:23], v[130:131]
	v_pk_mul_f32 v[24:25], v[24:25], v[132:133]
	v_pk_fma_f32 v[152:153], v[18:19], v[130:131], v[152:153] neg_lo:[0,0,1] neg_hi:[0,0,1]
	v_pk_fma_f32 v[154:155], v[20:21], v[132:133], v[154:155] neg_lo:[0,0,1] neg_hi:[0,0,1]
	v_pk_fma_f32 v[22:23], v[18:19], v[134:135], v[22:23]
	v_pk_fma_f32 v[24:25], v[20:21], v[136:137], v[24:25]
	v_cvt_pk_bf16_f32 v18, v152, v153
	v_cvt_pk_bf16_f32 v19, v154, v155
	v_cvt_pk_bf16_f32 v20, v22, v23
	v_cvt_pk_bf16_f32 v21, v24, v25
	v_add_u32_e32 v239, 0x28000, v189
	s_nop 1
	v_permlane16_swap_b32 v18, v20
	v_permlane16_swap_b32 v19, v21
	global_store_dwordx4 v239, v[18:21], s[78:79] offset:256
	v_pk_mul_f32 v[156:157], v[2:3], v[162:163]
	v_pk_mul_f32 v[168:169], v[4:5], v[164:165]
	v_pk_mul_f32 v[2:3], v[2:3], v[158:159]
	v_pk_mul_f32 v[4:5], v[4:5], v[160:161]
	v_pk_fma_f32 v[156:157], v[6:7], v[158:159], v[156:157] neg_lo:[0,0,1] neg_hi:[0,0,1]
	v_pk_fma_f32 v[168:169], v[8:9], v[160:161], v[168:169] neg_lo:[0,0,1] neg_hi:[0,0,1]
	v_pk_fma_f32 v[2:3], v[6:7], v[162:163], v[2:3]
	v_pk_fma_f32 v[4:5], v[8:9], v[164:165], v[4:5]
	v_cvt_pk_bf16_f32 v6, v156, v157
	v_cvt_pk_bf16_f32 v7, v168, v169
	v_cvt_pk_bf16_f32 v8, v2, v3
	v_cvt_pk_bf16_f32 v9, v4, v5
	v_add_u32_e32 v239, 0x2c000, v189
	s_nop 1
	v_permlane16_swap_b32 v6, v8
	v_permlane16_swap_b32 v7, v9
	global_store_dwordx4 v239, v[6:9], s[78:79] offset:256
	s_mov_b32 s32, 1
	s_branch .LBB0_323
.Lqk_k:
	s_lshl_b32 s2, s69, 3
	s_add_i32 s2, s2, s15
	s_mul_i32 s2, s2, 0x48000
	s_lshl_b32 s75, s71, 9
	s_add_i32 s2, s2, s75
	s_addk_i32 s2, 0x900
	s_add_u32 s4, s56, s2
	s_addc_u32 s5, s57, 0
	s_waitcnt vmcnt(0)
	s_add_u32 s8, s4, 0x2400
	s_addc_u32 s9, s5, 0
	s_add_u32 s10, s4, 0x24000
	s_addc_u32 s11, s5, 0
	s_add_u32 s12, s10, 0x2400
	s_addc_u32 s13, s11, 0
	v_pk_mul_f32 v[152:153], v[126:127], v[194:195]
	v_pk_mul_f32 v[154:155], v[128:129], v[196:197]
	v_pk_mul_f32 v[126:127], v[126:127], v[190:191]
	v_pk_mul_f32 v[128:129], v[128:129], v[192:193]
	v_pk_fma_f32 v[152:153], v[122:123], v[190:191], v[152:153] neg_lo:[0,0,1] neg_hi:[0,0,1]
	v_pk_fma_f32 v[154:155], v[124:125], v[192:193], v[154:155] neg_lo:[0,0,1] neg_hi:[0,0,1]
	v_pk_fma_f32 v[126:127], v[122:123], v[194:195], v[126:127]
	v_pk_fma_f32 v[128:129], v[124:125], v[196:197], v[128:129]
	v_pk_mul_f32 v[152:153], v[152:153], s[84:85] op_sel_hi:[1,0]
	v_pk_mul_f32 v[154:155], v[154:155], s[84:85] op_sel_hi:[1,0]
	v_pk_mul_f32 v[126:127], v[126:127], s[84:85] op_sel_hi:[1,0]
	v_pk_mul_f32 v[128:129], v[128:129], s[84:85] op_sel_hi:[1,0]
	v_cvt_pk_bf16_f32 v122, v152, v153
	v_cvt_pk_bf16_f32 v123, v154, v155
	v_cvt_pk_bf16_f32 v124, v126, v127
	v_cvt_pk_bf16_f32 v125, v128, v129
	global_store_short v238, v122, s[4:5] offset:-2304
	global_store_short_d16_hi v238, v122, s[4:5] offset:2304
	global_store_short v238, v123, s[8:9] offset:-2304
	global_store_short_d16_hi v238, v123, s[8:9] offset:2304
	global_store_short v238, v124, s[10:11] offset:-2304
	global_store_short_d16_hi v238, v124, s[10:11] offset:2304
	global_store_short v238, v125, s[12:13] offset:-2304
	global_store_short_d16_hi v238, v125, s[12:13] offset:2304
	s_nop 1
	v_permlane16_swap_b32 v122, v124
	v_permlane16_swap_b32 v123, v125
	global_store_dwordx4 v189, v[122:125], s[78:79]
	v_pk_mul_f32 v[156:157], v[110:111], v[202:203]
	v_pk_mul_f32 v[168:169], v[112:113], v[204:205]
	v_pk_mul_f32 v[110:111], v[110:111], v[198:199]
	v_pk_mul_f32 v[112:113], v[112:113], v[200:201]
	v_pk_fma_f32 v[156:157], v[106:107], v[198:199], v[156:157] neg_lo:[0,0,1] neg_hi:[0,0,1]
	v_pk_fma_f32 v[168:169], v[108:109], v[200:201], v[168:169] neg_lo:[0,0,1] neg_hi:[0,0,1]
	v_pk_fma_f32 v[110:111], v[106:107], v[202:203], v[110:111]
	v_pk_fma_f32 v[112:113], v[108:109], v[204:205], v[112:113]
	v_pk_mul_f32 v[156:157], v[156:157], s[84:85] op_sel_hi:[1,0]
	v_pk_mul_f32 v[168:169], v[168:169], s[84:85] op_sel_hi:[1,0]
	v_pk_mul_f32 v[110:111], v[110:111], s[84:85] op_sel_hi:[1,0]
	v_pk_mul_f32 v[112:113], v[112:113], s[84:85] op_sel_hi:[1,0]
	v_cvt_pk_bf16_f32 v106, v156, v157
	v_cvt_pk_bf16_f32 v107, v168, v169
	v_cvt_pk_bf16_f32 v108, v110, v111
	v_cvt_pk_bf16_f32 v109, v112, v113
	v_add_u32_e32 v239, 0x4000, v189
	global_store_short v238, v106, s[4:5] offset:-2272
	global_store_short_d16_hi v238, v106, s[4:5] offset:2336
	global_store_short v238, v107, s[8:9] offset:-2272
	global_store_short_d16_hi v238, v107, s[8:9] offset:2336
	global_store_short v238, v108, s[10:11] offset:-2272
	global_store_short_d16_hi v238, v108, s[10:11] offset:2336
	global_store_short v238, v109, s[12:13] offset:-2272
	global_store_short_d16_hi v238, v109, s[12:13] offset:2336
	s_nop 1
	v_permlane16_swap_b32 v106, v108
	v_permlane16_swap_b32 v107, v109
	global_store_dwordx4 v239, v[106:109], s[78:79]
	v_pk_mul_f32 v[152:153], v[94:95], v[210:211]
	v_pk_mul_f32 v[154:155], v[96:97], v[212:213]
	v_pk_mul_f32 v[94:95], v[94:95], v[206:207]
	v_pk_mul_f32 v[96:97], v[96:97], v[208:209]
	v_pk_fma_f32 v[152:153], v[90:91], v[206:207], v[152:153] neg_lo:[0,0,1] neg_hi:[0,0,1]
	v_pk_fma_f32 v[154:155], v[92:93], v[208:209], v[154:155] neg_lo:[0,0,1] neg_hi:[0,0,1]
	v_pk_fma_f32 v[94:95], v[90:91], v[210:211], v[94:95]
	v_pk_fma_f32 v[96:97], v[92:93], v[212:213], v[96:97]
	v_pk_mul_f32 v[152:153], v[152:153], s[84:85] op_sel_hi:[1,0]
	v_pk_mul_f32 v[154:155], v[154:155], s[84:85] op_sel_hi:[1,0]
	v_pk_mul_f32 v[94:95], v[94:95], s[84:85] op_sel_hi:[1,0]
	v_pk_mul_f32 v[96:97], v[96:97], s[84:85] op_sel_hi:[1,0]
	v_cvt_pk_bf16_f32 v90, v152, v153
	v_cvt_pk_bf16_f32 v91, v154, v155
; __device__ __forceinline__ unsigned pk2(float lo, float hi) { const f32x2_t v = {lo, hi}; const bf16v2_t b = __builtin_convertvector(v, bf16v2_t); return __builtin_bit_cast(unsigned, b); }
;     __device__ __forceinline__ void operator()(const AccT& acc, const pg8::Unit& u, int wr, int wc, int fr_, int fq_) const {
;     ...
; #pragma unroll
;                     for (int bj = 0; bj < 2; ++bj) {
;                         const int hq = 4 * (pn & 1) + 2 * bj + (wc >> 1);
;                         const f32x4 a1 = acc[ai][bj][m][0], a2 = acc[ai][bj][m][1];
;                         f32x4 o1 = a1 * cs - a2 * sn, o2 = a1 * sn + a2 * cs;
;                         if (isk) { o1 *= 0.125f; o2 *= 0.125f; }
;                         u32x2 p1, p2; p1.x = pk2(o1[0], o1[1]); p1.y = pk2(o1[2], o1[3]); p2.x = pk2(o2[0], o2[1]); p2.y = pk2(o2[2], o2[3]);
;                         bf16_t* dst = (isk ? KN : Q) + row * 512 + hq * 64 + jj0;
;                         *(u32x2*)dst = p1; *(u32x2*)(dst + 32) = p2;
;                         if (isk) {
;                             bf16_t* kt = KT + ((size_t)(b * NH + hq) * DK + jj0) * TB + pt * 256 + rl;
;                             kt[0] = (bf16_t)(p1.x & 0xffffu); kt[(size_t)TB] = (bf16_t)(p1.x >> 16); kt[(size_t)2 * TB] = (bf16_t)(p1.y & 0xffffu); kt[(size_t)3 * TB] = (bf16_t)(p1.y >> 16);
;                             bf16_t* kt2 = kt + (size_t)32 * TB;
;                             kt2[0] = (bf16_t)(p2.x & 0xffffu); kt2[(size_t)TB] = (bf16_t)(p2.x >> 16); kt2[(size_t)2 * TB] = (bf16_t)(p2.y & 0xffffu); kt2[(size_t)3 * TB] = (bf16_t)(p2.y >> 16);
;                         }
	v_cvt_pk_bf16_f32 v92, v94, v95
	v_cvt_pk_bf16_f32 v93, v96, v97
	v_add_u32_e32 v239, 0x8000, v189
	global_store_short v238, v90, s[4:5] offset:-2240
	global_store_short_d16_hi v238, v90, s[4:5] offset:2368
	global_store_short v238, v91, s[8:9] offset:-2240
	global_store_short_d16_hi v238, v91, s[8:9] offset:2368
	global_store_short v238, v92, s[10:11] offset:-2240
	global_store_short_d16_hi v238, v92, s[10:11] offset:2368
	global_store_short v238, v93, s[12:13] offset:-2240
	global_store_short_d16_hi v238, v93, s[12:13] offset:2368
	s_nop 1
	v_permlane16_swap_b32 v90, v92
	v_permlane16_swap_b32 v91, v93
	global_store_dwordx4 v239, v[90:93], s[78:79]
	v_pk_mul_f32 v[156:157], v[78:79], v[218:219]
	v_pk_mul_f32 v[168:169], v[80:81], v[220:221]
	v_pk_mul_f32 v[78:79], v[78:79], v[214:215]
	v_pk_mul_f32 v[80:81], v[80:81], v[216:217]
	v_pk_fma_f32 v[156:157], v[74:75], v[214:215], v[156:157] neg_lo:[0,0,1] neg_hi:[0,0,1]
	v_pk_fma_f32 v[168:169], v[76:77], v[216:217], v[168:169] neg_lo:[0,0,1] neg_hi:[0,0,1]
	v_pk_fma_f32 v[78:79], v[74:75], v[218:219], v[78:79]
	v_pk_fma_f32 v[80:81], v[76:77], v[220:221], v[80:81]
	v_pk_mul_f32 v[156:157], v[156:157], s[84:85] op_sel_hi:[1,0]
	v_pk_mul_f32 v[168:169], v[168:169], s[84:85] op_sel_hi:[1,0]
	v_pk_mul_f32 v[78:79], v[78:79], s[84:85] op_sel_hi:[1,0]
	v_pk_mul_f32 v[80:81], v[80:81], s[84:85] op_sel_hi:[1,0]
	v_cvt_pk_bf16_f32 v74, v156, v157
	v_cvt_pk_bf16_f32 v75, v168, v169
	v_cvt_pk_bf16_f32 v76, v78, v79
	v_cvt_pk_bf16_f32 v77, v80, v81
	v_add_u32_e32 v239, 0xc000, v189
	global_store_short v238, v74, s[4:5] offset:-2208
	global_store_short_d16_hi v238, v74, s[4:5] offset:2400
	global_store_short v238, v75, s[8:9] offset:-2208
	global_store_short_d16_hi v238, v75, s[8:9] offset:2400
	global_store_short v238, v76, s[10:11] offset:-2208
	global_store_short_d16_hi v238, v76, s[10:11] offset:2400
	global_store_short v238, v77, s[12:13] offset:-2208
	global_store_short_d16_hi v238, v77, s[12:13] offset:2400
	s_nop 1
	v_permlane16_swap_b32 v74, v76
	v_permlane16_swap_b32 v75, v77
	global_store_dwordx4 v239, v[74:77], s[78:79]
	v_pk_mul_f32 v[152:153], v[62:63], v[226:227]
	v_pk_mul_f32 v[154:155], v[64:65], v[228:229]
	v_pk_mul_f32 v[62:63], v[62:63], v[222:223]
	v_pk_mul_f32 v[64:65], v[64:65], v[224:225]
	v_pk_fma_f32 v[152:153], v[58:59], v[222:223], v[152:153] neg_lo:[0,0,1] neg_hi:[0,0,1]
	v_pk_fma_f32 v[154:155], v[60:61], v[224:225], v[154:155] neg_lo:[0,0,1] neg_hi:[0,0,1]
	v_pk_fma_f32 v[62:63], v[58:59], v[226:227], v[62:63]
	v_pk_fma_f32 v[64:65], v[60:61], v[228:229], v[64:65]
	v_pk_mul_f32 v[152:153], v[152:153], s[84:85] op_sel_hi:[1,0]
	v_pk_mul_f32 v[154:155], v[154:155], s[84:85] op_sel_hi:[1,0]
	v_pk_mul_f32 v[62:63], v[62:63], s[84:85] op_sel_hi:[1,0]
	v_pk_mul_f32 v[64:65], v[64:65], s[84:85] op_sel_hi:[1,0]
	v_cvt_pk_bf16_f32 v58, v152, v153
	v_cvt_pk_bf16_f32 v59, v154, v155
	v_cvt_pk_bf16_f32 v60, v62, v63
	v_cvt_pk_bf16_f32 v61, v64, v65
	v_add_u32_e32 v239, 0x20000, v189
	global_store_short v238, v58, s[4:5] offset:-2048
	global_store_short_d16_hi v238, v58, s[4:5] offset:2560
	global_store_short v238, v59, s[8:9] offset:-2048
	global_store_short_d16_hi v238, v59, s[8:9] offset:2560
	global_store_short v238, v60, s[10:11] offset:-2048
	global_store_short_d16_hi v238, v60, s[10:11] offset:2560
	global_store_short v238, v61, s[12:13] offset:-2048
	global_store_short_d16_hi v238, v61, s[12:13] offset:2560
	s_nop 1
	v_permlane16_swap_b32 v58, v60
	v_permlane16_swap_b32 v59, v61
	global_store_dwordx4 v239, v[58:61], s[78:79]
	v_pk_mul_f32 v[156:157], v[46:47], v[234:235]
	v_pk_mul_f32 v[168:169], v[48:49], v[236:237]
	v_pk_mul_f32 v[46:47], v[46:47], v[230:231]
	v_pk_mul_f32 v[48:49], v[48:49], v[232:233]
	v_pk_fma_f32 v[156:157], v[42:43], v[230:231], v[156:157] neg_lo:[0,0,1] neg_hi:[0,0,1]
	v_pk_fma_f32 v[168:169], v[44:45], v[232:233], v[168:169] neg_lo:[0,0,1] neg_hi:[0,0,1]
	v_pk_fma_f32 v[46:47], v[42:43], v[234:235], v[46:47]
	v_pk_fma_f32 v[48:49], v[44:45], v[236:237], v[48:49]
	v_pk_mul_f32 v[156:157], v[156:157], s[84:85] op_sel_hi:[1,0]
	v_pk_mul_f32 v[168:169], v[168:169], s[84:85] op_sel_hi:[1,0]
	v_pk_mul_f32 v[46:47], v[46:47], s[84:85] op_sel_hi:[1,0]
	v_pk_mul_f32 v[48:49], v[48:49], s[84:85] op_sel_hi:[1,0]
	v_cvt_pk_bf16_f32 v42, v156, v157
	v_cvt_pk_bf16_f32 v43, v168, v169
	v_cvt_pk_bf16_f32 v44, v46, v47
	v_cvt_pk_bf16_f32 v45, v48, v49
	v_add_u32_e32 v239, 0x24000, v189
	global_store_short v238, v42, s[4:5] offset:-2016
	global_store_short_d16_hi v238, v42, s[4:5] offset:2592
	global_store_short v238, v43, s[8:9] offset:-2016
	global_store_short_d16_hi v238, v43, s[8:9] offset:2592
	global_store_short v238, v44, s[10:11] offset:-2016
	global_store_short_d16_hi v238, v44, s[10:11] offset:2592
	global_store_short v238, v45, s[12:13] offset:-2016
	global_store_short_d16_hi v238, v45, s[12:13] offset:2592
	s_nop 1
	v_permlane16_swap_b32 v42, v44
	v_permlane16_swap_b32 v43, v45
	global_store_dwordx4 v239, v[42:45], s[78:79]
	v_pk_mul_f32 v[152:153], v[30:31], v[134:135]
	v_pk_mul_f32 v[154:155], v[32:33], v[136:137]
	v_pk_mul_f32 v[30:31], v[30:31], v[130:131]
	v_pk_mul_f32 v[32:33], v[32:33], v[132:133]
	v_pk_fma_f32 v[152:153], v[26:27], v[130:131], v[152:153] neg_lo:[0,0,1] neg_hi:[0,0,1]
	v_pk_fma_f32 v[154:155], v[28:29], v[132:133], v[154:155] neg_lo:[0,0,1] neg_hi:[0,0,1]
	v_pk_fma_f32 v[30:31], v[26:27], v[134:135], v[30:31]
	v_pk_fma_f32 v[32:33], v[28:29], v[136:137], v[32:33]
	v_pk_mul_f32 v[152:153], v[152:153], s[84:85] op_sel_hi:[1,0]
	v_pk_mul_f32 v[154:155], v[154:155], s[84:85] op_sel_hi:[1,0]
	v_pk_mul_f32 v[30:31], v[30:31], s[84:85] op_sel_hi:[1,0]
; __device__ __forceinline__ unsigned pk2(float lo, float hi) { const f32x2_t v = {lo, hi}; const bf16v2_t b = __builtin_convertvector(v, bf16v2_t); return __builtin_bit_cast(unsigned, b); }
;     __device__ __forceinline__ void operator()(const AccT& acc, const pg8::Unit& u, int wr, int wc, int fr_, int fq_) const {
;     ...
;                     f32x4 cs = (f32x4){1.f, 1.f, 1.f, 1.f}, sn = (f32x4){0.f, 0.f, 0.f, 0.f};
;                     if (pt != 0) { const int tpos = (pt - 1) * 256 + rl; cs = *(const f32x4*)(rope + (size_t)tpos * 32 + jj0); sn = *(const f32x4*)(rope + (size_t)SEQ * 32 + (size_t)tpos * 32 + jj0); }
; #pragma unroll
;                     for (int bj = 0; bj < 2; ++bj) {
;                         const int hq = 4 * (pn & 1) + 2 * bj + (wc >> 1);
;                         const f32x4 a1 = acc[ai][bj][m][0], a2 = acc[ai][bj][m][1];
;                         f32x4 o1 = a1 * cs - a2 * sn, o2 = a1 * sn + a2 * cs;
;                         if (isk) { o1 *= 0.125f; o2 *= 0.125f; }
;                         u32x2 p1, p2; p1.x = pk2(o1[0], o1[1]); p1.y = pk2(o1[2], o1[3]); p2.x = pk2(o2[0], o2[1]); p2.y = pk2(o2[2], o2[3]);
;                         bf16_t* dst = (isk ? KN : Q) + row * 512 + hq * 64 + jj0;
;                         *(u32x2*)dst = p1; *(u32x2*)(dst + 32) = p2;
;                         if (isk) {
;                             bf16_t* kt = KT + ((size_t)(b * NH + hq) * DK + jj0) * TB + pt * 256 + rl;
;                             kt[0] = (bf16_t)(p1.x & 0xffffu); kt[(size_t)TB] = (bf16_t)(p1.x >> 16); kt[(size_t)2 * TB] = (bf16_t)(p1.y & 0xffffu); kt[(size_t)3 * TB] = (bf16_t)(p1.y >> 16);
;                             bf16_t* kt2 = kt + (size_t)32 * TB;
;                             kt2[0] = (bf16_t)(p2.x & 0xffffu); kt2[(size_t)TB] = (bf16_t)(p2.x >> 16); kt2[(size_t)2 * TB] = (bf16_t)(p2.y & 0xffffu); kt2[(size_t)3 * TB] = (bf16_t)(p2.y >> 16);
;                         }
	v_pk_mul_f32 v[32:33], v[32:33], s[84:85] op_sel_hi:[1,0]
	v_cvt_pk_bf16_f32 v26, v152, v153
	v_cvt_pk_bf16_f32 v27, v154, v155
	v_cvt_pk_bf16_f32 v28, v30, v31
	v_cvt_pk_bf16_f32 v29, v32, v33
	v_add_u32_e32 v239, 0x28000, v189
	global_store_short v238, v26, s[4:5] offset:-1984
	global_store_short_d16_hi v238, v26, s[4:5] offset:2624
	global_store_short v238, v27, s[8:9] offset:-1984
	global_store_short_d16_hi v238, v27, s[8:9] offset:2624
	global_store_short v238, v28, s[10:11] offset:-1984
	global_store_short_d16_hi v238, v28, s[10:11] offset:2624
	global_store_short v238, v29, s[12:13] offset:-1984
	global_store_short_d16_hi v238, v29, s[12:13] offset:2624
	s_nop 1
	v_permlane16_swap_b32 v26, v28
	v_permlane16_swap_b32 v27, v29
	global_store_dwordx4 v239, v[26:29], s[78:79]
	v_pk_mul_f32 v[156:157], v[14:15], v[162:163]
	v_pk_mul_f32 v[168:169], v[16:17], v[164:165]
	v_pk_mul_f32 v[14:15], v[14:15], v[158:159]
	v_pk_mul_f32 v[16:17], v[16:17], v[160:161]
	v_pk_fma_f32 v[156:157], v[10:11], v[158:159], v[156:157] neg_lo:[0,0,1] neg_hi:[0,0,1]
	v_pk_fma_f32 v[168:169], v[12:13], v[160:161], v[168:169] neg_lo:[0,0,1] neg_hi:[0,0,1]
	v_pk_fma_f32 v[14:15], v[10:11], v[162:163], v[14:15]
	v_pk_fma_f32 v[16:17], v[12:13], v[164:165], v[16:17]
	v_pk_mul_f32 v[156:157], v[156:157], s[84:85] op_sel_hi:[1,0]
	v_pk_mul_f32 v[168:169], v[168:169], s[84:85] op_sel_hi:[1,0]
	v_pk_mul_f32 v[14:15], v[14:15], s[84:85] op_sel_hi:[1,0]
	v_pk_mul_f32 v[16:17], v[16:17], s[84:85] op_sel_hi:[1,0]
	v_cvt_pk_bf16_f32 v10, v156, v157
	v_cvt_pk_bf16_f32 v11, v168, v169
	v_cvt_pk_bf16_f32 v12, v14, v15
	v_cvt_pk_bf16_f32 v13, v16, v17
	v_add_u32_e32 v239, 0x2c000, v189
	global_store_short v238, v10, s[4:5] offset:-1952
	global_store_short_d16_hi v238, v10, s[4:5] offset:2656
	global_store_short v238, v11, s[8:9] offset:-1952
	global_store_short_d16_hi v238, v11, s[8:9] offset:2656
	global_store_short v238, v12, s[10:11] offset:-1952
	global_store_short_d16_hi v238, v12, s[10:11] offset:2656
	global_store_short v238, v13, s[12:13] offset:-1952
	global_store_short_d16_hi v238, v13, s[12:13] offset:2656
	s_nop 1
	v_permlane16_swap_b32 v10, v12
	v_permlane16_swap_b32 v11, v13
	global_store_dwordx4 v239, v[10:13], s[78:79]
	s_add_u32 s4, s4, 0x90000
	s_addc_u32 s5, s5, 0
	s_add_u32 s8, s4, 0x2400
	s_addc_u32 s9, s5, 0
	s_add_u32 s10, s4, 0x24000
	s_addc_u32 s11, s5, 0
	s_add_u32 s12, s10, 0x2400
	s_addc_u32 s13, s11, 0
	v_pk_mul_f32 v[152:153], v[118:119], v[194:195]
	v_pk_mul_f32 v[154:155], v[120:121], v[196:197]
	v_pk_mul_f32 v[118:119], v[118:119], v[190:191]
	v_pk_mul_f32 v[120:121], v[120:121], v[192:193]
	v_pk_fma_f32 v[152:153], v[114:115], v[190:191], v[152:153] neg_lo:[0,0,1] neg_hi:[0,0,1]
	v_pk_fma_f32 v[154:155], v[116:117], v[192:193], v[154:155] neg_lo:[0,0,1] neg_hi:[0,0,1]
	v_pk_fma_f32 v[118:119], v[114:115], v[194:195], v[118:119]
	v_pk_fma_f32 v[120:121], v[116:117], v[196:197], v[120:121]
	v_pk_mul_f32 v[152:153], v[152:153], s[84:85] op_sel_hi:[1,0]
	v_pk_mul_f32 v[154:155], v[154:155], s[84:85] op_sel_hi:[1,0]
	v_pk_mul_f32 v[118:119], v[118:119], s[84:85] op_sel_hi:[1,0]
	v_pk_mul_f32 v[120:121], v[120:121], s[84:85] op_sel_hi:[1,0]
	v_cvt_pk_bf16_f32 v114, v152, v153
	v_cvt_pk_bf16_f32 v115, v154, v155
	v_cvt_pk_bf16_f32 v116, v118, v119
	v_cvt_pk_bf16_f32 v117, v120, v121
	global_store_short v238, v114, s[4:5] offset:-2304
	global_store_short_d16_hi v238, v114, s[4:5] offset:2304
	global_store_short v238, v115, s[8:9] offset:-2304
	global_store_short_d16_hi v238, v115, s[8:9] offset:2304
	global_store_short v238, v116, s[10:11] offset:-2304
	global_store_short_d16_hi v238, v116, s[10:11] offset:2304
	global_store_short v238, v117, s[12:13] offset:-2304
	global_store_short_d16_hi v238, v117, s[12:13] offset:2304
	s_nop 1
	v_permlane16_swap_b32 v114, v116
	v_permlane16_swap_b32 v115, v117
	global_store_dwordx4 v189, v[114:117], s[78:79] offset:256
	v_pk_mul_f32 v[156:157], v[102:103], v[202:203]
	v_pk_mul_f32 v[168:169], v[104:105], v[204:205]
	v_pk_mul_f32 v[102:103], v[102:103], v[198:199]
	v_pk_mul_f32 v[104:105], v[104:105], v[200:201]
	v_pk_fma_f32 v[156:157], v[98:99], v[198:199], v[156:157] neg_lo:[0,0,1] neg_hi:[0,0,1]
	v_pk_fma_f32 v[168:169], v[100:101], v[200:201], v[168:169] neg_lo:[0,0,1] neg_hi:[0,0,1]
	v_pk_fma_f32 v[102:103], v[98:99], v[202:203], v[102:103]
	v_pk_fma_f32 v[104:105], v[100:101], v[204:205], v[104:105]
	v_pk_mul_f32 v[156:157], v[156:157], s[84:85] op_sel_hi:[1,0]
	v_pk_mul_f32 v[168:169], v[168:169], s[84:85] op_sel_hi:[1,0]
	v_pk_mul_f32 v[102:103], v[102:103], s[84:85] op_sel_hi:[1,0]
	v_pk_mul_f32 v[104:105], v[104:105], s[84:85] op_sel_hi:[1,0]
	v_cvt_pk_bf16_f32 v98, v156, v157
	v_cvt_pk_bf16_f32 v99, v168, v169
	v_cvt_pk_bf16_f32 v100, v102, v103
	v_cvt_pk_bf16_f32 v101, v104, v105
	v_add_u32_e32 v239, 0x4000, v189
	global_store_short v238, v98, s[4:5] offset:-2272
	global_store_short_d16_hi v238, v98, s[4:5] offset:2336
	global_store_short v238, v99, s[8:9] offset:-2272
	global_store_short_d16_hi v238, v99, s[8:9] offset:2336
	global_store_short v238, v100, s[10:11] offset:-2272
	global_store_short_d16_hi v238, v100, s[10:11] offset:2336
	global_store_short v238, v101, s[12:13] offset:-2272
	global_store_short_d16_hi v238, v101, s[12:13] offset:2336
	s_nop 1
	v_permlane16_swap_b32 v98, v100
	v_permlane16_swap_b32 v99, v101
	global_store_dwordx4 v239, v[98:101], s[78:79] offset:256
	v_pk_mul_f32 v[152:153], v[86:87], v[210:211]
	v_pk_mul_f32 v[154:155], v[88:89], v[212:213]
	v_pk_mul_f32 v[86:87], v[86:87], v[206:207]
	v_pk_mul_f32 v[88:89], v[88:89], v[208:209]
; __device__ __forceinline__ unsigned pk2(float lo, float hi) { const f32x2_t v = {lo, hi}; const bf16v2_t b = __builtin_convertvector(v, bf16v2_t); return __builtin_bit_cast(unsigned, b); }
;     __device__ __forceinline__ void operator()(const AccT& acc, const pg8::Unit& u, int wr, int wc, int fr_, int fq_) const {
;     ...
;                     f32x4 cs = (f32x4){1.f, 1.f, 1.f, 1.f}, sn = (f32x4){0.f, 0.f, 0.f, 0.f};
;                     if (pt != 0) { const int tpos = (pt - 1) * 256 + rl; cs = *(const f32x4*)(rope + (size_t)tpos * 32 + jj0); sn = *(const f32x4*)(rope + (size_t)SEQ * 32 + (size_t)tpos * 32 + jj0); }
; #pragma unroll
;                     for (int bj = 0; bj < 2; ++bj) {
;                         const int hq = 4 * (pn & 1) + 2 * bj + (wc >> 1);
;                         const f32x4 a1 = acc[ai][bj][m][0], a2 = acc[ai][bj][m][1];
;                         f32x4 o1 = a1 * cs - a2 * sn, o2 = a1 * sn + a2 * cs;
;                         if (isk) { o1 *= 0.125f; o2 *= 0.125f; }
;                         u32x2 p1, p2; p1.x = pk2(o1[0], o1[1]); p1.y = pk2(o1[2], o1[3]); p2.x = pk2(o2[0], o2[1]); p2.y = pk2(o2[2], o2[3]);
;                         bf16_t* dst = (isk ? KN : Q) + row * 512 + hq * 64 + jj0;
;                         *(u32x2*)dst = p1; *(u32x2*)(dst + 32) = p2;
;                         if (isk) {
;                             bf16_t* kt = KT + ((size_t)(b * NH + hq) * DK + jj0) * TB + pt * 256 + rl;
;                             kt[0] = (bf16_t)(p1.x & 0xffffu); kt[(size_t)TB] = (bf16_t)(p1.x >> 16); kt[(size_t)2 * TB] = (bf16_t)(p1.y & 0xffffu); kt[(size_t)3 * TB] = (bf16_t)(p1.y >> 16);
;                             bf16_t* kt2 = kt + (size_t)32 * TB;
;                             kt2[0] = (bf16_t)(p2.x & 0xffffu); kt2[(size_t)TB] = (bf16_t)(p2.x >> 16); kt2[(size_t)2 * TB] = (bf16_t)(p2.y & 0xffffu); kt2[(size_t)3 * TB] = (bf16_t)(p2.y >> 16);
;                         }
	v_pk_fma_f32 v[152:153], v[82:83], v[206:207], v[152:153] neg_lo:[0,0,1] neg_hi:[0,0,1]
	v_pk_fma_f32 v[154:155], v[84:85], v[208:209], v[154:155] neg_lo:[0,0,1] neg_hi:[0,0,1]
	v_pk_fma_f32 v[86:87], v[82:83], v[210:211], v[86:87]
	v_pk_fma_f32 v[88:89], v[84:85], v[212:213], v[88:89]
	v_pk_mul_f32 v[152:153], v[152:153], s[84:85] op_sel_hi:[1,0]
	v_pk_mul_f32 v[154:155], v[154:155], s[84:85] op_sel_hi:[1,0]
	v_pk_mul_f32 v[86:87], v[86:87], s[84:85] op_sel_hi:[1,0]
	v_pk_mul_f32 v[88:89], v[88:89], s[84:85] op_sel_hi:[1,0]
	v_cvt_pk_bf16_f32 v82, v152, v153
	v_cvt_pk_bf16_f32 v83, v154, v155
	v_cvt_pk_bf16_f32 v84, v86, v87
	v_cvt_pk_bf16_f32 v85, v88, v89
	v_add_u32_e32 v239, 0x8000, v189
	global_store_short v238, v82, s[4:5] offset:-2240
	global_store_short_d16_hi v238, v82, s[4:5] offset:2368
	global_store_short v238, v83, s[8:9] offset:-2240
	global_store_short_d16_hi v238, v83, s[8:9] offset:2368
	global_store_short v238, v84, s[10:11] offset:-2240
	global_store_short_d16_hi v238, v84, s[10:11] offset:2368
	global_store_short v238, v85, s[12:13] offset:-2240
	global_store_short_d16_hi v238, v85, s[12:13] offset:2368
	s_nop 1
	v_permlane16_swap_b32 v82, v84
	v_permlane16_swap_b32 v83, v85
	global_store_dwordx4 v239, v[82:85], s[78:79] offset:256
	v_pk_mul_f32 v[156:157], v[70:71], v[218:219]
	v_pk_mul_f32 v[168:169], v[72:73], v[220:221]
	v_pk_mul_f32 v[70:71], v[70:71], v[214:215]
	v_pk_mul_f32 v[72:73], v[72:73], v[216:217]
	v_pk_fma_f32 v[156:157], v[66:67], v[214:215], v[156:157] neg_lo:[0,0,1] neg_hi:[0,0,1]
	v_pk_fma_f32 v[168:169], v[68:69], v[216:217], v[168:169] neg_lo:[0,0,1] neg_hi:[0,0,1]
	v_pk_fma_f32 v[70:71], v[66:67], v[218:219], v[70:71]
	v_pk_fma_f32 v[72:73], v[68:69], v[220:221], v[72:73]
	v_pk_mul_f32 v[156:157], v[156:157], s[84:85] op_sel_hi:[1,0]
	v_pk_mul_f32 v[168:169], v[168:169], s[84:85] op_sel_hi:[1,0]
	v_pk_mul_f32 v[70:71], v[70:71], s[84:85] op_sel_hi:[1,0]
	v_pk_mul_f32 v[72:73], v[72:73], s[84:85] op_sel_hi:[1,0]
	v_cvt_pk_bf16_f32 v66, v156, v157
	v_cvt_pk_bf16_f32 v67, v168, v169
	v_cvt_pk_bf16_f32 v68, v70, v71
	v_cvt_pk_bf16_f32 v69, v72, v73
	v_add_u32_e32 v239, 0xc000, v189
	global_store_short v238, v66, s[4:5] offset:-2208
	global_store_short_d16_hi v238, v66, s[4:5] offset:2400
	global_store_short v238, v67, s[8:9] offset:-2208
	global_store_short_d16_hi v238, v67, s[8:9] offset:2400
	global_store_short v238, v68, s[10:11] offset:-2208
	global_store_short_d16_hi v238, v68, s[10:11] offset:2400
	global_store_short v238, v69, s[12:13] offset:-2208
	global_store_short_d16_hi v238, v69, s[12:13] offset:2400
	s_nop 1
	v_permlane16_swap_b32 v66, v68
	v_permlane16_swap_b32 v67, v69
	global_store_dwordx4 v239, v[66:69], s[78:79] offset:256
	v_pk_mul_f32 v[152:153], v[54:55], v[226:227]
	v_pk_mul_f32 v[154:155], v[56:57], v[228:229]
	v_pk_mul_f32 v[54:55], v[54:55], v[222:223]
	v_pk_mul_f32 v[56:57], v[56:57], v[224:225]
	v_pk_fma_f32 v[152:153], v[50:51], v[222:223], v[152:153] neg_lo:[0,0,1] neg_hi:[0,0,1]
	v_pk_fma_f32 v[154:155], v[52:53], v[224:225], v[154:155] neg_lo:[0,0,1] neg_hi:[0,0,1]
	v_pk_fma_f32 v[54:55], v[50:51], v[226:227], v[54:55]
	v_pk_fma_f32 v[56:57], v[52:53], v[228:229], v[56:57]
	v_pk_mul_f32 v[152:153], v[152:153], s[84:85] op_sel_hi:[1,0]
	v_pk_mul_f32 v[154:155], v[154:155], s[84:85] op_sel_hi:[1,0]
	v_pk_mul_f32 v[54:55], v[54:55], s[84:85] op_sel_hi:[1,0]
	v_pk_mul_f32 v[56:57], v[56:57], s[84:85] op_sel_hi:[1,0]
	v_cvt_pk_bf16_f32 v50, v152, v153
	v_cvt_pk_bf16_f32 v51, v154, v155
	v_cvt_pk_bf16_f32 v52, v54, v55
	v_cvt_pk_bf16_f32 v53, v56, v57
	v_add_u32_e32 v239, 0x20000, v189
	global_store_short v238, v50, s[4:5] offset:-2048
	global_store_short_d16_hi v238, v50, s[4:5] offset:2560
	global_store_short v238, v51, s[8:9] offset:-2048
	global_store_short_d16_hi v238, v51, s[8:9] offset:2560
	global_store_short v238, v52, s[10:11] offset:-2048
	global_store_short_d16_hi v238, v52, s[10:11] offset:2560
	global_store_short v238, v53, s[12:13] offset:-2048
	global_store_short_d16_hi v238, v53, s[12:13] offset:2560
	s_nop 1
	v_permlane16_swap_b32 v50, v52
	v_permlane16_swap_b32 v51, v53
	global_store_dwordx4 v239, v[50:53], s[78:79] offset:256
	v_pk_mul_f32 v[156:157], v[38:39], v[234:235]
	v_pk_mul_f32 v[168:169], v[40:41], v[236:237]
; __device__ __forceinline__ unsigned pk2(float lo, float hi) { const f32x2_t v = {lo, hi}; const bf16v2_t b = __builtin_convertvector(v, bf16v2_t); return __builtin_bit_cast(unsigned, b); }
;     __device__ __forceinline__ void operator()(const AccT& acc, const pg8::Unit& u, int wr, int wc, int fr_, int fq_) const {
;     ...
;                     f32x4 cs = (f32x4){1.f, 1.f, 1.f, 1.f}, sn = (f32x4){0.f, 0.f, 0.f, 0.f};
;                     if (pt != 0) { const int tpos = (pt - 1) * 256 + rl; cs = *(const f32x4*)(rope + (size_t)tpos * 32 + jj0); sn = *(const f32x4*)(rope + (size_t)SEQ * 32 + (size_t)tpos * 32 + jj0); }
; #pragma unroll
;                     for (int bj = 0; bj < 2; ++bj) {
;                         const int hq = 4 * (pn & 1) + 2 * bj + (wc >> 1);
;                         const f32x4 a1 = acc[ai][bj][m][0], a2 = acc[ai][bj][m][1];
;                         f32x4 o1 = a1 * cs - a2 * sn, o2 = a1 * sn + a2 * cs;
;                         if (isk) { o1 *= 0.125f; o2 *= 0.125f; }
;                         u32x2 p1, p2; p1.x = pk2(o1[0], o1[1]); p1.y = pk2(o1[2], o1[3]); p2.x = pk2(o2[0], o2[1]); p2.y = pk2(o2[2], o2[3]);
;                         bf16_t* dst = (isk ? KN : Q) + row * 512 + hq * 64 + jj0;
;                         *(u32x2*)dst = p1; *(u32x2*)(dst + 32) = p2;
;                         if (isk) {
;                             bf16_t* kt = KT + ((size_t)(b * NH + hq) * DK + jj0) * TB + pt * 256 + rl;
;                             kt[0] = (bf16_t)(p1.x & 0xffffu); kt[(size_t)TB] = (bf16_t)(p1.x >> 16); kt[(size_t)2 * TB] = (bf16_t)(p1.y & 0xffffu); kt[(size_t)3 * TB] = (bf16_t)(p1.y >> 16);
;                             bf16_t* kt2 = kt + (size_t)32 * TB;
;                             kt2[0] = (bf16_t)(p2.x & 0xffffu); kt2[(size_t)TB] = (bf16_t)(p2.x >> 16); kt2[(size_t)2 * TB] = (bf16_t)(p2.y & 0xffffu); kt2[(size_t)3 * TB] = (bf16_t)(p2.y >> 16);
;                         }
	v_pk_mul_f32 v[38:39], v[38:39], v[230:231]
	v_pk_mul_f32 v[40:41], v[40:41], v[232:233]
	v_pk_fma_f32 v[156:157], v[34:35], v[230:231], v[156:157] neg_lo:[0,0,1] neg_hi:[0,0,1]
	v_pk_fma_f32 v[168:169], v[36:37], v[232:233], v[168:169] neg_lo:[0,0,1] neg_hi:[0,0,1]
	v_pk_fma_f32 v[38:39], v[34:35], v[234:235], v[38:39]
	v_pk_fma_f32 v[40:41], v[36:37], v[236:237], v[40:41]
	v_pk_mul_f32 v[156:157], v[156:157], s[84:85] op_sel_hi:[1,0]
	v_pk_mul_f32 v[168:169], v[168:169], s[84:85] op_sel_hi:[1,0]
	v_pk_mul_f32 v[38:39], v[38:39], s[84:85] op_sel_hi:[1,0]
	v_pk_mul_f32 v[40:41], v[40:41], s[84:85] op_sel_hi:[1,0]
	v_cvt_pk_bf16_f32 v34, v156, v157
	v_cvt_pk_bf16_f32 v35, v168, v169
	v_cvt_pk_bf16_f32 v36, v38, v39
	v_cvt_pk_bf16_f32 v37, v40, v41
	v_add_u32_e32 v239, 0x24000, v189
	global_store_short v238, v34, s[4:5] offset:-2016
	global_store_short_d16_hi v238, v34, s[4:5] offset:2592
	global_store_short v238, v35, s[8:9] offset:-2016
	global_store_short_d16_hi v238, v35, s[8:9] offset:2592
	global_store_short v238, v36, s[10:11] offset:-2016
	global_store_short_d16_hi v238, v36, s[10:11] offset:2592
	global_store_short v238, v37, s[12:13] offset:-2016
	global_store_short_d16_hi v238, v37, s[12:13] offset:2592
	s_nop 1
	v_permlane16_swap_b32 v34, v36
	v_permlane16_swap_b32 v35, v37
	global_store_dwordx4 v239, v[34:37], s[78:79] offset:256
	v_pk_mul_f32 v[152:153], v[22:23], v[134:135]
	v_pk_mul_f32 v[154:155], v[24:25], v[136:137]
	v_pk_mul_f32 v[22:23], v[22:23], v[130:131]
	v_pk_mul_f32 v[24:25], v[24:25], v[132:133]
	v_pk_fma_f32 v[152:153], v[18:19], v[130:131], v[152:153] neg_lo:[0,0,1] neg_hi:[0,0,1]
	v_pk_fma_f32 v[154:155], v[20:21], v[132:133], v[154:155] neg_lo:[0,0,1] neg_hi:[0,0,1]
	v_pk_fma_f32 v[22:23], v[18:19], v[134:135], v[22:23]
	v_pk_fma_f32 v[24:25], v[20:21], v[136:137], v[24:25]
	v_pk_mul_f32 v[152:153], v[152:153], s[84:85] op_sel_hi:[1,0]
	v_pk_mul_f32 v[154:155], v[154:155], s[84:85] op_sel_hi:[1,0]
	v_pk_mul_f32 v[22:23], v[22:23], s[84:85] op_sel_hi:[1,0]
	v_pk_mul_f32 v[24:25], v[24:25], s[84:85] op_sel_hi:[1,0]
	v_cvt_pk_bf16_f32 v18, v152, v153
	v_cvt_pk_bf16_f32 v19, v154, v155
	v_cvt_pk_bf16_f32 v20, v22, v23
	v_cvt_pk_bf16_f32 v21, v24, v25
	v_add_u32_e32 v239, 0x28000, v189
	global_store_short v238, v18, s[4:5] offset:-1984
	global_store_short_d16_hi v238, v18, s[4:5] offset:2624
	global_store_short v238, v19, s[8:9] offset:-1984
	global_store_short_d16_hi v238, v19, s[8:9] offset:2624
	global_store_short v238, v20, s[10:11] offset:-1984
	global_store_short_d16_hi v238, v20, s[10:11] offset:2624
	global_store_short v238, v21, s[12:13] offset:-1984
	global_store_short_d16_hi v238, v21, s[12:13] offset:2624
	s_nop 1
	v_permlane16_swap_b32 v18, v20
	v_permlane16_swap_b32 v19, v21
	global_store_dwordx4 v239, v[18:21], s[78:79] offset:256
	v_pk_mul_f32 v[156:157], v[2:3], v[162:163]
	v_pk_mul_f32 v[168:169], v[4:5], v[164:165]
	v_pk_mul_f32 v[2:3], v[2:3], v[158:159]
	v_pk_mul_f32 v[4:5], v[4:5], v[160:161]
	v_pk_fma_f32 v[156:157], v[6:7], v[158:159], v[156:157] neg_lo:[0,0,1] neg_hi:[0,0,1]
	v_pk_fma_f32 v[168:169], v[8:9], v[160:161], v[168:169] neg_lo:[0,0,1] neg_hi:[0,0,1]
	v_pk_fma_f32 v[2:3], v[6:7], v[162:163], v[2:3]
	v_pk_fma_f32 v[4:5], v[8:9], v[164:165], v[4:5]
	v_pk_mul_f32 v[156:157], v[156:157], s[84:85] op_sel_hi:[1,0]
	v_pk_mul_f32 v[168:169], v[168:169], s[84:85] op_sel_hi:[1,0]
	v_pk_mul_f32 v[2:3], v[2:3], s[84:85] op_sel_hi:[1,0]
	v_pk_mul_f32 v[4:5], v[4:5], s[84:85] op_sel_hi:[1,0]
	v_cvt_pk_bf16_f32 v6, v156, v157
	v_cvt_pk_bf16_f32 v7, v168, v169
	v_cvt_pk_bf16_f32 v8, v2, v3
	v_cvt_pk_bf16_f32 v9, v4, v5
	v_add_u32_e32 v239, 0x2c000, v189
	global_store_short v238, v6, s[4:5] offset:-1952
	global_store_short_d16_hi v238, v6, s[4:5] offset:2656
	global_store_short v238, v7, s[8:9] offset:-1952
	global_store_short_d16_hi v238, v7, s[8:9] offset:2656
	global_store_short v238, v8, s[10:11] offset:-1952
	global_store_short_d16_hi v238, v8, s[10:11] offset:2656
	global_store_short v238, v9, s[12:13] offset:-1952
	global_store_short_d16_hi v238, v9, s[12:13] offset:2656
	s_nop 1
	v_permlane16_swap_b32 v6, v8
	v_permlane16_swap_b32 v7, v9
	global_store_dwordx4 v239, v[6:9], s[78:79] offset:256
	s_mov_b32 s32, 3
	s_branch .LBB0_323
